# p3a S1: per-token sum of squares by one packed multiply, three packed FMAs and one add instead of four packed squares and seven scalar adds
# baseline (speedup 1.0000x reference)
.Lp3a_s2h_skip:
	v_pk_fma_f32 v[52:53], v[110:111], v[48:49], v[52:53]
	v_pk_add_f32 v[226:227], v[226:227], 1.0 op_sel_hi:[1,0]
	v_pk_mul_f32 v[228:229], v[52:53], v[246:247] op_sel_hi:[1,0]
	v_rcp_f32_e32 v226, v226
	v_rcp_f32_e32 v227, v227
	v_exp_f32_e32 v228, v228
	v_exp_f32_e32 v229, v229
	v_lshlrev_b32_e32 v28, 16, v121
	v_pk_mul_f32 v[22:23], v[22:23], v[226:227]
	v_pk_add_f32 v[228:229], v[228:229], 1.0 op_sel_hi:[1,0]
	v_lshlrev_b32_e32 v54, 16, v117
	v_and_b32_e32 v55, 0xffff0000, v117
	v_and_b32_e32 v29, 0xffff0000, v121
	v_pk_fma_f32 v[54:55], v[4:5], v[54:55], 0 op_sel_hi:[1,1,0]
	v_lshlrev_b32_e32 v36, 16, v125
	v_and_b32_e32 v37, 0xffff0000, v125
	v_pk_fma_f32 v[54:55], v[16:17], v[28:29], v[54:55]
	v_lshlrev_b32_e32 v44, 16, v129
	v_and_b32_e32 v45, 0xffff0000, v129
	v_pk_fma_f32 v[54:55], v[104:105], v[36:37], v[54:55]
	v_rcp_f32_e32 v228, v228
	v_pk_fma_f32 v[54:55], v[112:113], v[44:45], v[54:55]
	v_rcp_f32_e32 v229, v229
	v_pk_mul_f32 v[226:227], v[54:55], v[246:247] op_sel_hi:[1,0]
	v_exp_f32_e32 v226, v226
	v_exp_f32_e32 v227, v227
	v_pk_mul_f32 v[232:233], v[20:21], v[20:21]
	v_pk_fma_f32 v[232:233], v[22:23], v[22:23], v[232:233]
	v_pk_add_f32 v[226:227], v[226:227], 1.0 op_sel_hi:[1,0]
	v_rcp_f32_e32 v226, v226
	v_rcp_f32_e32 v227, v227
	v_pk_mul_f32 v[52:53], v[52:53], v[228:229]
	v_and_b32_e32 v167, 64, v184
	v_pk_fma_f32 v[232:233], v[52:53], v[52:53], v[232:233]
	v_xor_b32_e32 v19, 1, v184
	v_add_u32_e32 v60, 64, v167
	v_pk_mul_f32 v[54:55], v[54:55], v[226:227]
	v_cmp_lt_i32_e32 vcc, v19, v60
	v_pk_fma_f32 v[232:233], v[54:55], v[54:55], v[232:233]
	v_cndmask_b32_e32 v19, v184, v19, vcc
	v_lshlrev_b32_e32 v19, 2, v19
	v_add_f32_e32 v24, v232, v233
	v_xor_b32_e32 v26, 2, v184
	v_cmp_lt_i32_e32 vcc, v26, v60
	v_mov_b32_e32 v160, v1
	s_nop 1
	v_add_f32_dpp v24, v24, v24 quad_perm:[1,0,3,2] row_mask:0xf bank_mask:0xf
	v_cndmask_b32_e32 v26, v184, v26, vcc
	v_lshlrev_b32_e32 v168, 2, v26
	v_xor_b32_e32 v26, 4, v184
	v_cmp_lt_i32_e32 vcc, v26, v60
	v_cmp_gt_i32_e64 s[6:7], 16, v160
	v_mov_b32_e32 v56, 1.0
	v_cndmask_b32_e32 v26, v184, v26, vcc
	v_lshlrev_b32_e32 v173, 2, v26
	s_nop 1
	v_add_f32_dpp v24, v24, v24 quad_perm:[2,3,0,1] row_mask:0xf bank_mask:0xf
	v_xor_b32_e32 v26, 8, v184
	v_cmp_lt_i32_e32 vcc, v26, v60
	v_cndmask_b32_e64 v161, 1.0, v187, s[6:7]
	v_cmp_gt_i32_e64 s[4:5], 32, v160
	v_cndmask_b32_e32 v26, v184, v26, vcc
	v_lshlrev_b32_e32 v175, 2, v26
	s_nop 1
	v_add_f32_dpp v24, v24, v24 row_half_mirror row_mask:0xf bank_mask:0xf
	s_nop 1
	v_add_f32_dpp v24, v24, v24 row_mirror row_mask:0xf bank_mask:0xf
	s_and_saveexec_b64 s[8:9], s[4:5]
	s_cbranch_execz .LBB0_502
	v_add_f32_e32 v24, 0x358637bd, v24
	v_mul_f32_e32 v25, 0x4b800000, v24
	v_cmp_gt_f32_e32 vcc, s48, v24
	s_nop 1
	v_cndmask_b32_e32 v24, v24, v25, vcc
	v_rsq_f32_e32 v24, v24
	s_nop 0
	v_mul_f32_e32 v25, 0x45800000, v24
	v_cndmask_b32_e32 v24, v24, v25, vcc
	v_mul_f32_e32 v56, v161, v24

.LBB0_504:
	s_or_b64 exec, exec, s[8:9]
	v_pk_fma_f32 v[34:35], v[6:7], v[34:35], 0 op_sel_hi:[1,1,0]
	v_lshlrev_b32_e32 v60, 16, v130
	v_pk_fma_f32 v[34:35], v[10:11], v[42:43], v[34:35]
	v_and_b32_e32 v61, 0xffff0000, v130
	v_pk_fma_f32 v[34:35], v[98:99], v[50:51], v[34:35]
	v_pk_fma_f32 v[32:33], v[8:9], v[32:33], 0 op_sel_hi:[1,1,0]
	v_pk_fma_f32 v[34:35], v[106:107], v[60:61], v[34:35]
	v_pk_fma_f32 v[32:33], v[12:13], v[40:41], v[32:33]
	v_pk_mul_f32 v[226:227], v[34:35], v[246:247] op_sel_hi:[1,0]
	v_exp_f32_e32 v226, v226
	v_exp_f32_e32 v227, v227
	v_lshlrev_b32_e32 v58, 16, v131
	v_and_b32_e32 v59, 0xffff0000, v131
	v_pk_add_f32 v[226:227], v[226:227], 1.0 op_sel_hi:[1,0]
	v_rcp_f32_e32 v226, v226
	v_rcp_f32_e32 v227, v227
	v_pk_fma_f32 v[32:33], v[100:101], v[46:47], v[32:33]
	v_pk_fma_f32 v[30:31], v[2:3], v[30:31], 0 op_sel_hi:[1,1,0]
	v_pk_fma_f32 v[32:33], v[108:109], v[58:59], v[32:33]
	v_pk_mul_f32 v[34:35], v[34:35], v[226:227]
	v_pk_mul_f32 v[226:227], v[32:33], v[246:247] op_sel_hi:[1,0]
	v_exp_f32_e32 v226, v226
	v_exp_f32_e32 v227, v227
	v_pk_fma_f32 v[30:31], v[14:15], v[38:39], v[30:31]
	v_lshlrev_b32_e32 v62, 16, v132
	v_pk_add_f32 v[226:227], v[226:227], 1.0 op_sel_hi:[1,0]
	v_and_b32_e32 v63, 0xffff0000, v132
	v_rcp_f32_e32 v226, v226
	v_rcp_f32_e32 v227, v227
	v_pk_fma_f32 v[30:31], v[102:103], v[48:49], v[30:31]
	v_pk_fma_f32 v[28:29], v[4:5], v[28:29], 0 op_sel_hi:[1,1,0]
	v_pk_fma_f32 v[64:65], v[110:111], v[62:63], v[30:31]
	v_pk_fma_f32 v[28:29], v[16:17], v[36:37], v[28:29]
	v_pk_mul_f32 v[228:229], v[64:65], v[246:247] op_sel_hi:[1,0]
	v_lshlrev_b32_e32 v56, 16, v133
	v_and_b32_e32 v57, 0xffff0000, v133
	v_exp_f32_e32 v228, v228
	v_pk_fma_f32 v[28:29], v[104:105], v[44:45], v[28:29]
	v_exp_f32_e32 v229, v229
	v_pk_mul_f32 v[30:31], v[32:33], v[226:227]
	v_pk_fma_f32 v[52:53], v[112:113], v[56:57], v[28:29]
	v_pk_mul_f32 v[226:227], v[52:53], v[246:247] op_sel_hi:[1,0]
	v_exp_f32_e32 v226, v226
	v_exp_f32_e32 v227, v227
	v_pk_add_f32 v[228:229], v[228:229], 1.0 op_sel_hi:[1,0]
	v_rcp_f32_e32 v228, v228
	v_rcp_f32_e32 v229, v229
	v_pk_add_f32 v[226:227], v[226:227], 1.0 op_sel_hi:[1,0]
	v_rcp_f32_e32 v226, v226
	v_pk_mul_f32 v[234:235], v[34:35], v[34:35]
	v_rcp_f32_e32 v227, v227
	v_pk_fma_f32 v[234:235], v[30:31], v[30:31], v[234:235]
	v_pk_mul_f32 v[28:29], v[64:65], v[228:229]
	v_pk_fma_f32 v[234:235], v[28:29], v[28:29], v[234:235]
	v_pk_mul_f32 v[52:53], v[52:53], v[226:227]
	v_pk_fma_f32 v[234:235], v[52:53], v[52:53], v[234:235]
	v_add_f32_e32 v32, v234, v235
	v_mov_b32_e32 v54, 1.0
	s_nop 1
	v_add_f32_dpp v32, v32, v32 quad_perm:[1,0,3,2] row_mask:0xf bank_mask:0xf
	s_nop 1
	v_add_f32_dpp v32, v32, v32 quad_perm:[2,3,0,1] row_mask:0xf bank_mask:0xf
	s_nop 1
	v_add_f32_dpp v32, v32, v32 row_half_mirror row_mask:0xf bank_mask:0xf
	s_nop 1
	v_add_f32_dpp v32, v32, v32 row_mirror row_mask:0xf bank_mask:0xf
	s_and_saveexec_b64 s[8:9], s[4:5]
	s_cbranch_execz .LBB0_506
	v_add_f32_e32 v32, 0x358637bd, v32
	v_mul_f32_e32 v33, 0x4b800000, v32
	v_cmp_gt_f32_e32 vcc, s48, v32
	s_nop 1
	v_cndmask_b32_e32 v32, v32, v33, vcc
	v_rsq_f32_e32 v32, v32
	s_nop 0
	v_mul_f32_e32 v33, 0x45800000, v32
	v_cndmask_b32_e32 v32, v32, v33, vcc
	v_mul_f32_e32 v54, v161, v32

.LBB0_508:
	s_or_b64 exec, exec, s[8:9]
	v_pk_fma_f32 v[42:43], v[6:7], v[42:43], 0 op_sel_hi:[1,1,0]
	v_lshlrev_b32_e32 v80, 16, v134
	v_pk_fma_f32 v[42:43], v[10:11], v[50:51], v[42:43]
	v_and_b32_e32 v81, 0xffff0000, v134
	v_pk_fma_f32 v[42:43], v[98:99], v[60:61], v[42:43]
	v_pk_fma_f32 v[40:41], v[8:9], v[40:41], 0 op_sel_hi:[1,1,0]
	v_pk_fma_f32 v[42:43], v[106:107], v[80:81], v[42:43]
	v_pk_fma_f32 v[40:41], v[12:13], v[46:47], v[40:41]
	v_pk_mul_f32 v[226:227], v[42:43], v[246:247] op_sel_hi:[1,0]
	v_exp_f32_e32 v226, v226
	v_exp_f32_e32 v227, v227
	v_lshlrev_b32_e32 v66, 16, v135
	v_and_b32_e32 v67, 0xffff0000, v135
	v_pk_add_f32 v[226:227], v[226:227], 1.0 op_sel_hi:[1,0]
	v_rcp_f32_e32 v226, v226
	v_rcp_f32_e32 v227, v227
	v_pk_fma_f32 v[40:41], v[100:101], v[58:59], v[40:41]
	v_pk_fma_f32 v[38:39], v[2:3], v[38:39], 0 op_sel_hi:[1,1,0]
	v_pk_fma_f32 v[40:41], v[108:109], v[66:67], v[40:41]
	v_pk_mul_f32 v[42:43], v[42:43], v[226:227]
	v_pk_mul_f32 v[226:227], v[40:41], v[246:247] op_sel_hi:[1,0]
	v_exp_f32_e32 v226, v226
	v_exp_f32_e32 v227, v227
	v_pk_fma_f32 v[38:39], v[14:15], v[48:49], v[38:39]
	v_lshlrev_b32_e32 v72, 16, v136
	v_pk_add_f32 v[226:227], v[226:227], 1.0 op_sel_hi:[1,0]
	v_and_b32_e32 v73, 0xffff0000, v136
	v_rcp_f32_e32 v226, v226
	v_rcp_f32_e32 v227, v227
	v_pk_fma_f32 v[38:39], v[102:103], v[62:63], v[38:39]
	v_pk_fma_f32 v[36:37], v[4:5], v[36:37], 0 op_sel_hi:[1,1,0]
	v_pk_fma_f32 v[68:69], v[110:111], v[72:73], v[38:39]
	v_pk_fma_f32 v[36:37], v[16:17], v[44:45], v[36:37]
	v_pk_mul_f32 v[228:229], v[68:69], v[246:247] op_sel_hi:[1,0]
	v_lshlrev_b32_e32 v54, 16, v137
	v_and_b32_e32 v55, 0xffff0000, v137
	v_exp_f32_e32 v228, v228
	v_pk_fma_f32 v[36:37], v[104:105], v[56:57], v[36:37]
	v_exp_f32_e32 v229, v229
	v_pk_mul_f32 v[38:39], v[40:41], v[226:227]
	v_pk_fma_f32 v[52:53], v[112:113], v[54:55], v[36:37]
	v_pk_mul_f32 v[226:227], v[52:53], v[246:247] op_sel_hi:[1,0]
	v_exp_f32_e32 v226, v226
	v_exp_f32_e32 v227, v227
	v_pk_add_f32 v[228:229], v[228:229], 1.0 op_sel_hi:[1,0]
	v_rcp_f32_e32 v228, v228
	v_rcp_f32_e32 v229, v229
	v_pk_add_f32 v[226:227], v[226:227], 1.0 op_sel_hi:[1,0]
	v_rcp_f32_e32 v226, v226
	v_pk_mul_f32 v[236:237], v[42:43], v[42:43]
	v_rcp_f32_e32 v227, v227
	v_pk_fma_f32 v[236:237], v[38:39], v[38:39], v[236:237]
	v_pk_mul_f32 v[36:37], v[68:69], v[228:229]
	v_pk_fma_f32 v[236:237], v[36:37], v[36:37], v[236:237]
	v_pk_mul_f32 v[52:53], v[52:53], v[226:227]
	v_pk_fma_f32 v[236:237], v[52:53], v[52:53], v[236:237]
	v_add_f32_e32 v40, v236, v237
	v_mov_b32_e32 v64, 1.0
	s_nop 1
	v_add_f32_dpp v40, v40, v40 quad_perm:[1,0,3,2] row_mask:0xf bank_mask:0xf
	s_nop 1
	v_add_f32_dpp v40, v40, v40 quad_perm:[2,3,0,1] row_mask:0xf bank_mask:0xf
	s_nop 1
	v_add_f32_dpp v40, v40, v40 row_half_mirror row_mask:0xf bank_mask:0xf
	s_nop 1
	v_add_f32_dpp v40, v40, v40 row_mirror row_mask:0xf bank_mask:0xf
	s_and_saveexec_b64 s[8:9], s[4:5]
	s_cbranch_execz .LBB0_510
	v_add_f32_e32 v40, 0x358637bd, v40
	v_mul_f32_e32 v41, 0x4b800000, v40
	v_cmp_gt_f32_e32 vcc, s48, v40
	s_nop 1
	v_cndmask_b32_e32 v40, v40, v41, vcc
	v_rsq_f32_e32 v40, v40
	s_nop 0
	v_mul_f32_e32 v41, 0x45800000, v40
	v_cndmask_b32_e32 v40, v40, v41, vcc
	v_mul_f32_e32 v64, v161, v40

.LBB0_512:
	s_or_b64 exec, exec, s[8:9]
	v_pk_fma_f32 v[50:51], v[6:7], v[50:51], 0 op_sel_hi:[1,1,0]
	v_lshlrev_b32_e32 v78, 16, v138
	v_pk_fma_f32 v[50:51], v[10:11], v[60:61], v[50:51]
	v_and_b32_e32 v79, 0xffff0000, v138
	v_pk_fma_f32 v[50:51], v[98:99], v[80:81], v[50:51]
	v_pk_fma_f32 v[46:47], v[8:9], v[46:47], 0 op_sel_hi:[1,1,0]
	v_pk_fma_f32 v[50:51], v[106:107], v[78:79], v[50:51]
	v_pk_fma_f32 v[46:47], v[12:13], v[58:59], v[46:47]
	v_pk_mul_f32 v[226:227], v[50:51], v[246:247] op_sel_hi:[1,0]
	v_exp_f32_e32 v226, v226
	v_exp_f32_e32 v227, v227
	v_lshlrev_b32_e32 v64, 16, v139
	v_pk_add_f32 v[226:227], v[226:227], 1.0 op_sel_hi:[1,0]
	v_rcp_f32_e32 v226, v226
	v_rcp_f32_e32 v227, v227
	v_and_b32_e32 v65, 0xffff0000, v139
	v_pk_fma_f32 v[46:47], v[100:101], v[66:67], v[46:47]
	v_pk_fma_f32 v[48:49], v[2:3], v[48:49], 0 op_sel_hi:[1,1,0]
	v_pk_fma_f32 v[46:47], v[108:109], v[64:65], v[46:47]
	v_pk_mul_f32 v[50:51], v[50:51], v[226:227]
	v_pk_mul_f32 v[226:227], v[46:47], v[246:247] op_sel_hi:[1,0]
	v_exp_f32_e32 v226, v226
	v_exp_f32_e32 v227, v227
	v_pk_fma_f32 v[48:49], v[14:15], v[62:63], v[48:49]
	v_lshlrev_b32_e32 v70, 16, v140
	v_and_b32_e32 v71, 0xffff0000, v140
	v_pk_fma_f32 v[48:49], v[102:103], v[72:73], v[48:49]
	v_pk_fma_f32 v[48:49], v[110:111], v[70:71], v[48:49]
	v_pk_add_f32 v[226:227], v[226:227], 1.0 op_sel_hi:[1,0]
	v_pk_mul_f32 v[228:229], v[48:49], v[246:247] op_sel_hi:[1,0]
	v_rcp_f32_e32 v226, v226
	v_rcp_f32_e32 v227, v227
	v_exp_f32_e32 v228, v228
	v_exp_f32_e32 v229, v229
	v_pk_fma_f32 v[44:45], v[4:5], v[44:45], 0 op_sel_hi:[1,1,0]
	v_lshlrev_b32_e32 v52, 16, v141
	v_pk_fma_f32 v[44:45], v[16:17], v[56:57], v[44:45]
	v_and_b32_e32 v53, 0xffff0000, v141
	v_pk_fma_f32 v[44:45], v[104:105], v[54:55], v[44:45]
	v_pk_mul_f32 v[46:47], v[46:47], v[226:227]
	v_pk_add_f32 v[228:229], v[228:229], 1.0 op_sel_hi:[1,0]
	v_pk_fma_f32 v[76:77], v[112:113], v[52:53], v[44:45]
	v_rcp_f32_e32 v228, v228
	v_pk_mul_f32 v[226:227], v[76:77], v[246:247] op_sel_hi:[1,0]
	v_exp_f32_e32 v226, v226
	v_exp_f32_e32 v227, v227
	v_rcp_f32_e32 v229, v229
	v_pk_add_f32 v[226:227], v[226:227], 1.0 op_sel_hi:[1,0]
	v_rcp_f32_e32 v226, v226
	v_pk_mul_f32 v[238:239], v[50:51], v[50:51]
	v_rcp_f32_e32 v227, v227
	v_pk_fma_f32 v[238:239], v[46:47], v[46:47], v[238:239]
	v_pk_mul_f32 v[44:45], v[48:49], v[228:229]
	v_pk_fma_f32 v[238:239], v[44:45], v[44:45], v[238:239]
	v_pk_mul_f32 v[68:69], v[76:77], v[226:227]
	v_pk_fma_f32 v[238:239], v[68:69], v[68:69], v[238:239]
	v_add_f32_e32 v48, v238, v239
	v_mov_b32_e32 v74, 1.0
	s_nop 1
	v_add_f32_dpp v48, v48, v48 quad_perm:[1,0,3,2] row_mask:0xf bank_mask:0xf
	s_nop 1
	v_add_f32_dpp v48, v48, v48 quad_perm:[2,3,0,1] row_mask:0xf bank_mask:0xf
	s_nop 1
	v_add_f32_dpp v48, v48, v48 row_half_mirror row_mask:0xf bank_mask:0xf
	s_nop 1
	v_add_f32_dpp v48, v48, v48 row_mirror row_mask:0xf bank_mask:0xf
	s_and_saveexec_b64 s[8:9], s[4:5]
	s_cbranch_execz .LBB0_514
	v_add_f32_e32 v48, 0x358637bd, v48
	v_mul_f32_e32 v49, 0x4b800000, v48
	v_cmp_gt_f32_e32 vcc, s48, v48
	s_nop 1
	v_cndmask_b32_e32 v48, v48, v49, vcc
	v_rsq_f32_e32 v48, v48
	s_nop 0
	v_mul_f32_e32 v49, 0x45800000, v48
	v_cndmask_b32_e32 v48, v48, v49, vcc
	v_mul_f32_e32 v74, v161, v48

.LBB0_516:
	s_or_b64 exec, exec, s[8:9]
	v_pk_fma_f32 v[60:61], v[6:7], v[60:61], 0 op_sel_hi:[1,1,0]
	v_lshlrev_b32_e32 v82, 16, v142
	v_pk_fma_f32 v[60:61], v[10:11], v[80:81], v[60:61]
	v_and_b32_e32 v83, 0xffff0000, v142
	v_pk_fma_f32 v[60:61], v[98:99], v[78:79], v[60:61]
	v_pk_fma_f32 v[58:59], v[8:9], v[58:59], 0 op_sel_hi:[1,1,0]
	v_pk_fma_f32 v[68:69], v[106:107], v[82:83], v[60:61]
	v_pk_fma_f32 v[58:59], v[12:13], v[66:67], v[58:59]
	v_pk_mul_f32 v[226:227], v[68:69], v[246:247] op_sel_hi:[1,0]
	v_exp_f32_e32 v226, v226
	v_exp_f32_e32 v227, v227
	v_lshlrev_b32_e32 v76, 16, v143
	v_pk_add_f32 v[226:227], v[226:227], 1.0 op_sel_hi:[1,0]
	v_rcp_f32_e32 v226, v226
	v_rcp_f32_e32 v227, v227
	v_and_b32_e32 v77, 0xffff0000, v143
	v_pk_fma_f32 v[58:59], v[100:101], v[64:65], v[58:59]
	v_pk_fma_f32 v[62:63], v[2:3], v[62:63], 0 op_sel_hi:[1,1,0]
	v_pk_fma_f32 v[58:59], v[108:109], v[76:77], v[58:59]
	v_pk_mul_f32 v[68:69], v[68:69], v[226:227]
	v_pk_mul_f32 v[226:227], v[58:59], v[246:247] op_sel_hi:[1,0]
	v_exp_f32_e32 v226, v226
	v_exp_f32_e32 v227, v227
	v_pk_fma_f32 v[62:63], v[14:15], v[72:73], v[62:63]
	v_lshlrev_b32_e32 v74, 16, v144
	v_and_b32_e32 v75, 0xffff0000, v144
	v_pk_fma_f32 v[62:63], v[102:103], v[70:71], v[62:63]
	v_pk_fma_f32 v[62:63], v[110:111], v[74:75], v[62:63]
	v_pk_add_f32 v[226:227], v[226:227], 1.0 op_sel_hi:[1,0]
	v_pk_mul_f32 v[228:229], v[62:63], v[246:247] op_sel_hi:[1,0]
	v_rcp_f32_e32 v226, v226
	v_rcp_f32_e32 v227, v227
	v_exp_f32_e32 v228, v228
	v_exp_f32_e32 v229, v229
	v_pk_fma_f32 v[56:57], v[4:5], v[56:57], 0 op_sel_hi:[1,1,0]
	v_lshlrev_b32_e32 v60, 16, v145
	v_pk_fma_f32 v[56:57], v[16:17], v[54:55], v[56:57]
	v_and_b32_e32 v61, 0xffff0000, v145
	v_pk_fma_f32 v[56:57], v[104:105], v[52:53], v[56:57]
	v_pk_mul_f32 v[58:59], v[58:59], v[226:227]
	v_pk_add_f32 v[228:229], v[228:229], 1.0 op_sel_hi:[1,0]
	v_pk_fma_f32 v[88:89], v[112:113], v[60:61], v[56:57]
	v_rcp_f32_e32 v228, v228
	v_pk_mul_f32 v[226:227], v[88:89], v[246:247] op_sel_hi:[1,0]
	v_exp_f32_e32 v226, v226
	v_exp_f32_e32 v227, v227
	v_rcp_f32_e32 v229, v229
	v_pk_add_f32 v[226:227], v[226:227], 1.0 op_sel_hi:[1,0]
	v_rcp_f32_e32 v226, v226
	v_pk_mul_f32 v[232:233], v[68:69], v[68:69]
	v_rcp_f32_e32 v227, v227
	v_pk_fma_f32 v[232:233], v[58:59], v[58:59], v[232:233]
	v_pk_mul_f32 v[56:57], v[62:63], v[228:229]
	v_pk_fma_f32 v[232:233], v[56:57], v[56:57], v[232:233]
	v_pk_mul_f32 v[84:85], v[88:89], v[226:227]
	v_pk_fma_f32 v[232:233], v[84:85], v[84:85], v[232:233]
	v_add_f32_e32 v62, v232, v233
	v_mov_b32_e32 v86, 1.0
	s_nop 1
	v_add_f32_dpp v62, v62, v62 quad_perm:[1,0,3,2] row_mask:0xf bank_mask:0xf
	s_nop 1
	v_add_f32_dpp v62, v62, v62 quad_perm:[2,3,0,1] row_mask:0xf bank_mask:0xf
	s_nop 1
	v_add_f32_dpp v62, v62, v62 row_half_mirror row_mask:0xf bank_mask:0xf
	s_nop 1
	v_add_f32_dpp v62, v62, v62 row_mirror row_mask:0xf bank_mask:0xf
	s_and_saveexec_b64 s[8:9], s[4:5]
	s_cbranch_execz .LBB0_518
	v_add_f32_e32 v62, 0x358637bd, v62
	v_mul_f32_e32 v63, 0x4b800000, v62
	v_cmp_gt_f32_e32 vcc, s48, v62
	s_nop 1
	v_cndmask_b32_e32 v62, v62, v63, vcc
	v_rsq_f32_e32 v62, v62
	s_nop 0
	v_mul_f32_e32 v63, 0x45800000, v62
	v_cndmask_b32_e32 v62, v62, v63, vcc
	v_mul_f32_e32 v86, v161, v62

.LBB0_520:
	s_or_b64 exec, exec, s[8:9]
	v_pk_fma_f32 v[80:81], v[6:7], v[80:81], 0 op_sel_hi:[1,1,0]
	v_lshlrev_b32_e32 v90, 16, v146
	v_pk_fma_f32 v[80:81], v[10:11], v[78:79], v[80:81]
	v_and_b32_e32 v91, 0xffff0000, v146
	v_pk_fma_f32 v[80:81], v[98:99], v[82:83], v[80:81]
	v_pk_fma_f32 v[66:67], v[8:9], v[66:67], 0 op_sel_hi:[1,1,0]
	v_pk_fma_f32 v[84:85], v[106:107], v[90:91], v[80:81]
	v_pk_fma_f32 v[66:67], v[12:13], v[64:65], v[66:67]
	v_pk_mul_f32 v[226:227], v[84:85], v[246:247] op_sel_hi:[1,0]
	v_exp_f32_e32 v226, v226
	v_exp_f32_e32 v227, v227
	v_lshlrev_b32_e32 v88, 16, v147
	v_pk_add_f32 v[226:227], v[226:227], 1.0 op_sel_hi:[1,0]
	v_rcp_f32_e32 v226, v226
	v_rcp_f32_e32 v227, v227
	v_and_b32_e32 v89, 0xffff0000, v147
	v_pk_fma_f32 v[66:67], v[100:101], v[76:77], v[66:67]
	v_pk_fma_f32 v[72:73], v[2:3], v[72:73], 0 op_sel_hi:[1,1,0]
	v_pk_fma_f32 v[66:67], v[108:109], v[88:89], v[66:67]
	v_pk_mul_f32 v[84:85], v[84:85], v[226:227]
	v_pk_mul_f32 v[226:227], v[66:67], v[246:247] op_sel_hi:[1,0]
	v_exp_f32_e32 v226, v226
	v_exp_f32_e32 v227, v227
	v_pk_fma_f32 v[72:73], v[14:15], v[70:71], v[72:73]
	v_lshlrev_b32_e32 v86, 16, v148
	v_and_b32_e32 v87, 0xffff0000, v148
	v_pk_fma_f32 v[72:73], v[102:103], v[74:75], v[72:73]
	v_pk_fma_f32 v[72:73], v[110:111], v[86:87], v[72:73]
	v_pk_add_f32 v[226:227], v[226:227], 1.0 op_sel_hi:[1,0]
	v_pk_mul_f32 v[228:229], v[72:73], v[246:247] op_sel_hi:[1,0]
	v_rcp_f32_e32 v226, v226
	v_rcp_f32_e32 v227, v227
	v_exp_f32_e32 v228, v228
	v_exp_f32_e32 v229, v229
	v_pk_fma_f32 v[54:55], v[4:5], v[54:55], 0 op_sel_hi:[1,1,0]
	v_lshlrev_b32_e32 v80, 16, v149
	v_pk_fma_f32 v[54:55], v[16:17], v[52:53], v[54:55]
	v_and_b32_e32 v81, 0xffff0000, v149
	v_pk_fma_f32 v[54:55], v[104:105], v[60:61], v[54:55]
	v_pk_mul_f32 v[66:67], v[66:67], v[226:227]
	v_pk_add_f32 v[228:229], v[228:229], 1.0 op_sel_hi:[1,0]
	v_pk_fma_f32 v[96:97], v[112:113], v[80:81], v[54:55]
	v_rcp_f32_e32 v228, v228
	v_pk_mul_f32 v[226:227], v[96:97], v[246:247] op_sel_hi:[1,0]
	v_exp_f32_e32 v226, v226
	v_exp_f32_e32 v227, v227
	v_rcp_f32_e32 v229, v229
	v_pk_add_f32 v[226:227], v[226:227], 1.0 op_sel_hi:[1,0]
	v_rcp_f32_e32 v226, v226
	v_pk_mul_f32 v[234:235], v[84:85], v[84:85]
	v_rcp_f32_e32 v227, v227
	v_pk_fma_f32 v[234:235], v[66:67], v[66:67], v[234:235]
	v_pk_mul_f32 v[54:55], v[72:73], v[228:229]
	v_pk_fma_f32 v[234:235], v[54:55], v[54:55], v[234:235]
	v_pk_mul_f32 v[92:93], v[96:97], v[226:227]
	v_pk_fma_f32 v[234:235], v[92:93], v[92:93], v[234:235]
	v_add_f32_e32 v72, v234, v235
	v_mov_b32_e32 v94, 1.0
	s_nop 1
	v_add_f32_dpp v72, v72, v72 quad_perm:[1,0,3,2] row_mask:0xf bank_mask:0xf
	s_nop 1
	v_add_f32_dpp v72, v72, v72 quad_perm:[2,3,0,1] row_mask:0xf bank_mask:0xf
	s_nop 1
	v_add_f32_dpp v72, v72, v72 row_half_mirror row_mask:0xf bank_mask:0xf
	s_nop 1
	v_add_f32_dpp v72, v72, v72 row_mirror row_mask:0xf bank_mask:0xf
	s_and_saveexec_b64 s[8:9], s[4:5]
	s_cbranch_execz .LBB0_522
	v_add_f32_e32 v72, 0x358637bd, v72
	v_mul_f32_e32 v73, 0x4b800000, v72
	v_cmp_gt_f32_e32 vcc, s48, v72
	s_nop 1
	v_cndmask_b32_e32 v72, v72, v73, vcc
	v_rsq_f32_e32 v72, v72
	s_nop 0
	v_mul_f32_e32 v73, 0x45800000, v72
	v_cndmask_b32_e32 v72, v72, v73, vcc
	v_mul_f32_e32 v94, v161, v72

.LBB0_524:
	s_or_b64 exec, exec, s[8:9]
	v_pk_fma_f32 v[78:79], v[6:7], v[78:79], 0 op_sel_hi:[1,1,0]
	v_lshlrev_b32_e32 v162, 16, v150
	v_pk_fma_f32 v[78:79], v[10:11], v[82:83], v[78:79]
	v_and_b32_e32 v163, 0xffff0000, v150
	v_pk_fma_f32 v[78:79], v[98:99], v[90:91], v[78:79]
	v_pk_fma_f32 v[64:65], v[8:9], v[64:65], 0 op_sel_hi:[1,1,0]
	v_pk_fma_f32 v[78:79], v[106:107], v[162:163], v[78:79]
	v_pk_fma_f32 v[64:65], v[12:13], v[76:77], v[64:65]
	v_pk_mul_f32 v[226:227], v[78:79], v[246:247] op_sel_hi:[1,0]
	v_exp_f32_e32 v226, v226
	v_exp_f32_e32 v227, v227
	v_lshlrev_b32_e32 v96, 16, v151
	v_pk_add_f32 v[226:227], v[226:227], 1.0 op_sel_hi:[1,0]
	v_rcp_f32_e32 v226, v226
	v_rcp_f32_e32 v227, v227
	v_and_b32_e32 v97, 0xffff0000, v151
	v_pk_fma_f32 v[64:65], v[100:101], v[88:89], v[64:65]
	v_pk_fma_f32 v[70:71], v[2:3], v[70:71], 0 op_sel_hi:[1,1,0]
	v_pk_fma_f32 v[64:65], v[108:109], v[96:97], v[64:65]
	v_pk_mul_f32 v[78:79], v[78:79], v[226:227]
	v_pk_mul_f32 v[226:227], v[64:65], v[246:247] op_sel_hi:[1,0]
	v_exp_f32_e32 v226, v226
	v_exp_f32_e32 v227, v227
	v_pk_fma_f32 v[70:71], v[14:15], v[74:75], v[70:71]
	v_lshlrev_b32_e32 v94, 16, v152
	v_and_b32_e32 v95, 0xffff0000, v152
	v_pk_fma_f32 v[70:71], v[102:103], v[86:87], v[70:71]
	v_pk_fma_f32 v[70:71], v[110:111], v[94:95], v[70:71]
	v_pk_add_f32 v[226:227], v[226:227], 1.0 op_sel_hi:[1,0]
	v_pk_mul_f32 v[228:229], v[70:71], v[246:247] op_sel_hi:[1,0]
	v_rcp_f32_e32 v226, v226
	v_rcp_f32_e32 v227, v227
	v_exp_f32_e32 v228, v228
	v_pk_fma_f32 v[52:53], v[4:5], v[52:53], 0 op_sel_hi:[1,1,0]
	v_exp_f32_e32 v229, v229
	v_pk_fma_f32 v[52:53], v[16:17], v[60:61], v[52:53]
	v_lshlrev_b32_e32 v92, 16, v153
	v_and_b32_e32 v93, 0xffff0000, v153
	v_pk_fma_f32 v[52:53], v[104:105], v[80:81], v[52:53]
	v_pk_mul_f32 v[64:65], v[64:65], v[226:227]
	v_pk_fma_f32 v[52:53], v[112:113], v[92:93], v[52:53]
	v_pk_mul_f32 v[226:227], v[52:53], v[246:247] op_sel_hi:[1,0]
	v_pk_add_f32 v[228:229], v[228:229], 1.0 op_sel_hi:[1,0]
	v_exp_f32_e32 v226, v226
	v_exp_f32_e32 v227, v227
	v_rcp_f32_e32 v228, v228
	v_rcp_f32_e32 v229, v229
	v_pk_add_f32 v[226:227], v[226:227], 1.0 op_sel_hi:[1,0]
	v_rcp_f32_e32 v226, v226
	v_pk_mul_f32 v[236:237], v[78:79], v[78:79]
	v_rcp_f32_e32 v227, v227
	v_pk_fma_f32 v[236:237], v[64:65], v[64:65], v[236:237]
	v_pk_mul_f32 v[70:71], v[70:71], v[228:229]
	v_pk_fma_f32 v[236:237], v[70:71], v[70:71], v[236:237]
	v_pk_mul_f32 v[164:165], v[52:53], v[226:227]
	v_pk_fma_f32 v[236:237], v[164:165], v[164:165], v[236:237]
	v_add_f32_e32 v52, v236, v237
	v_mov_b32_e32 v166, 1.0
	s_nop 1
	v_add_f32_dpp v52, v52, v52 quad_perm:[1,0,3,2] row_mask:0xf bank_mask:0xf
	s_nop 1
	v_add_f32_dpp v52, v52, v52 quad_perm:[2,3,0,1] row_mask:0xf bank_mask:0xf
	s_nop 1
	v_add_f32_dpp v52, v52, v52 row_half_mirror row_mask:0xf bank_mask:0xf
	s_nop 1
	v_add_f32_dpp v52, v52, v52 row_mirror row_mask:0xf bank_mask:0xf
	s_and_saveexec_b64 s[8:9], s[4:5]
	s_cbranch_execz .LBB0_526
	v_add_f32_e32 v52, 0x358637bd, v52
	v_mul_f32_e32 v53, 0x4b800000, v52
	v_cmp_gt_f32_e32 vcc, s48, v52
	s_nop 1
	v_cndmask_b32_e32 v52, v52, v53, vcc
	v_rsq_f32_e32 v52, v52
	s_nop 0
	v_mul_f32_e32 v53, 0x45800000, v52
	v_cndmask_b32_e32 v52, v52, v53, vcc
	v_mul_f32_e32 v166, v161, v52

.LBB0_528:
	s_or_b64 exec, exec, s[8:9]
	v_pk_fma_f32 v[82:83], v[6:7], v[82:83], 0 op_sel_hi:[1,1,0]
	v_pk_fma_f32 v[76:77], v[8:9], v[76:77], 0 op_sel_hi:[1,1,0]
	v_pk_fma_f32 v[82:83], v[10:11], v[90:91], v[82:83]
	v_lshlrev_b32_e32 v90, 16, v154
	v_pk_fma_f32 v[82:83], v[98:99], v[162:163], v[82:83]
	v_and_b32_e32 v91, 0xffff0000, v154
	v_pk_fma_f32 v[82:83], v[106:107], v[90:91], v[82:83]
	v_pk_fma_f32 v[76:77], v[12:13], v[88:89], v[76:77]
	v_pk_mul_f32 v[226:227], v[82:83], v[246:247] op_sel_hi:[1,0]
	v_exp_f32_e32 v226, v226
	v_exp_f32_e32 v227, v227
	v_pk_fma_f32 v[76:77], v[100:101], v[96:97], v[76:77]
	v_lshlrev_b32_e32 v88, 16, v155
	v_pk_add_f32 v[226:227], v[226:227], 1.0 op_sel_hi:[1,0]
	v_rcp_f32_e32 v226, v226
	v_rcp_f32_e32 v227, v227
	v_and_b32_e32 v89, 0xffff0000, v155
	v_pk_fma_f32 v[76:77], v[108:109], v[88:89], v[76:77]
	v_pk_fma_f32 v[74:75], v[2:3], v[74:75], 0 op_sel_hi:[1,1,0]
	v_pk_mul_f32 v[228:229], v[76:77], v[246:247] op_sel_hi:[1,0]
	v_pk_mul_f32 v[82:83], v[82:83], v[226:227]
	v_exp_f32_e32 v228, v228
	v_exp_f32_e32 v229, v229
	v_pk_fma_f32 v[74:75], v[14:15], v[86:87], v[74:75]
	v_lshlrev_b32_e32 v86, 16, v156
	v_pk_fma_f32 v[74:75], v[102:103], v[94:95], v[74:75]
	v_and_b32_e32 v87, 0xffff0000, v156
	v_pk_fma_f32 v[86:87], v[110:111], v[86:87], v[74:75]
	v_pk_fma_f32 v[60:61], v[4:5], v[60:61], 0 op_sel_hi:[1,1,0]
	v_pk_mul_f32 v[226:227], v[86:87], v[246:247] op_sel_hi:[1,0]
	v_pk_fma_f32 v[60:61], v[16:17], v[80:81], v[60:61]
	v_pk_add_f32 v[228:229], v[228:229], 1.0 op_sel_hi:[1,0]
	v_exp_f32_e32 v226, v226
	v_pk_fma_f32 v[60:61], v[104:105], v[92:93], v[60:61]
	v_lshlrev_b32_e32 v80, 16, v157
	v_and_b32_e32 v81, 0xffff0000, v157
	v_rcp_f32_e32 v228, v228
	v_rcp_f32_e32 v229, v229
	v_exp_f32_e32 v227, v227
	v_pk_fma_f32 v[60:61], v[112:113], v[80:81], v[60:61]
	v_pk_mul_f32 v[238:239], v[82:83], v[82:83]
	v_pk_mul_f32 v[230:231], v[60:61], v[246:247] op_sel_hi:[1,0]
	v_exp_f32_e32 v230, v230
	v_exp_f32_e32 v231, v231
	v_pk_mul_f32 v[74:75], v[76:77], v[228:229]
	v_pk_add_f32 v[226:227], v[226:227], 1.0 op_sel_hi:[1,0]
	v_rcp_f32_e32 v226, v226
	v_rcp_f32_e32 v227, v227
	v_pk_add_f32 v[230:231], v[230:231], 1.0 op_sel_hi:[1,0]
	v_rcp_f32_e32 v230, v230
	v_rcp_f32_e32 v231, v231
	v_pk_fma_f32 v[238:239], v[74:75], v[74:75], v[238:239]
	v_pk_mul_f32 v[76:77], v[86:87], v[226:227]
	v_pk_fma_f32 v[238:239], v[76:77], v[76:77], v[238:239]
	v_pk_mul_f32 v[80:81], v[60:61], v[230:231]
	v_pk_fma_f32 v[238:239], v[80:81], v[80:81], v[238:239]
	v_add_f32_e32 v60, v238, v239
	v_mov_b32_e32 v86, 1.0
	s_nop 1
	v_add_f32_dpp v19, v60, v60 quad_perm:[1,0,3,2] row_mask:0xf bank_mask:0xf
	s_nop 1
	v_add_f32_dpp v19, v19, v19 quad_perm:[2,3,0,1] row_mask:0xf bank_mask:0xf
	s_nop 1
	v_add_f32_dpp v19, v19, v19 row_half_mirror row_mask:0xf bank_mask:0xf
	s_nop 1
	v_add_f32_dpp v19, v19, v19 row_mirror row_mask:0xf bank_mask:0xf
	s_and_saveexec_b64 s[8:9], s[4:5]
	s_cbranch_execz .LBB0_530
	v_add_f32_e32 v19, 0x358637bd, v19
	v_mul_f32_e32 v60, 0x4b800000, v19
	v_cmp_gt_f32_e32 vcc, s48, v19
	s_nop 1
	v_cndmask_b32_e32 v19, v19, v60, vcc
	v_rsq_f32_e32 v19, v19
	s_nop 0
	v_mul_f32_e32 v60, 0x45800000, v19
	v_cndmask_b32_e32 v19, v19, v60, vcc
	v_mul_f32_e32 v86, v161, v19
